# attention heads: drop self-max canonicalisations (exact for non-NaN) and the duplicate running-max copy; 3 fewer dependent VALU per tile
# baseline (speedup 1.0000x reference)
.Lattn1_nomask:
	s_add_i32 s9, s78, 0x10000
	s_and_b32 s33, s9, 0x18000
	s_and_b32 s76, s78, 0x18000
	v_add_u32_e32 v250, s33, v237
	v_add_u32_e32 v250, v250, v228
	ds_read_b128 v[128:131], v250 offset:16384
	ds_read_b128 v[132:135], v250 offset:20480
	ds_read_b128 v[136:139], v250 offset:24576
	ds_read_b128 v[140:143], v250 offset:28672
	v_add_u32_e32 v251, s76, v235
	v_add_u32_e32 v250, v251, v228
	ds_read_b128 v[144:147], v250
	ds_read_b128 v[148:151], v250 offset:4096
	v_add_u32_e32 v250, v251, v231
	ds_read_b128 v[152:155], v250
	ds_read_b128 v[156:159], v250 offset:4096
	s_add_i32 s0, s74, s38
	s_addk_i32 s0, 0xc0
	s_mul_i32 s0, s0, s14
	s_lshl_b32 s92, s46, 1
	s_add_i32 s0, s0, s92
	s_addk_i32 s0, 0x1c00
	s_add_u32 s98, s82, s0
	s_addc_u32 s99, s83, 0
	s_add_i32 s0, s78, 0x8000
	s_and_b32 s0, s0, 0x18000
	s_add_i32 s0, s5, s0
	s_mov_b32 m0, s0
	s_nop 0
	global_load_lds_dwordx4 v244, s[98:99]
	s_add_i32 m0, s0, 0x2000
	s_add_u32 s98, s98, 0x80
	s_addc_u32 s99, s99, 0
	global_load_lds_dwordx4 v244, s[98:99]
	s_lshl_b32 s1, s17, 13
	s_add_u32 s98, s40, s1
	s_addc_u32 s99, s41, 0
	s_add_i32 m0, s0, 0x4000
	s_nop 0
	global_load_lds_dwordx4 v245, s[98:99]
	s_add_i32 m0, s0, 0x6000
	s_add_u32 s98, s98, 0x80000
	s_addc_u32 s99, s99, 0
	global_load_lds_dwordx4 v245, s[98:99]
	v_max3_f32 v246, v64, v65, v66
	v_max3_f32 v247, v72, v73, v74
	v_max3_f32 v248, v80, v81, v82
	v_max3_f32 v249, v88, v89, v90
	v_max3_f32 v246, v246, v67, v68
	v_max3_f32 v247, v247, v75, v76
	v_max3_f32 v248, v248, v83, v84
	v_max3_f32 v249, v249, v91, v92
	s_waitcnt lgkmcnt(7)
	v_mfma_f32_32x32x16_bf16 v[0:15], v[128:131], v[96:99], v[0:15]
	v_max3_f32 v246, v246, v69, v70
	v_max3_f32 v247, v247, v77, v78
	v_max3_f32 v248, v248, v85, v86
	v_max3_f32 v249, v249, v93, v94
	v_max3_f32 v246, v246, v71, v247
	v_max3_f32 v247, v248, v87, v249
	s_waitcnt lgkmcnt(6)
	v_mfma_f32_32x32x16_bf16 v[48:63], v[132:135], v[96:99], v[48:63]
	v_max3_f32 v246, v246, v79, v95
	s_nop 0
	v_max3_f32 v246, v246, v247, v247
	s_nop 0
	v_mov_b32_e32 v247, v246
	s_nop 1
	v_permlane32_swap_b32_e32 v246, v247
	v_max3_f32 v246, v246, v247, v247
	s_nop 0
	v_max_f32_e32 v251, v212, v246
	s_waitcnt lgkmcnt(5)
	v_mfma_f32_32x32x16_bf16 v[32:47], v[136:139], v[96:99], v[32:47]
	v_sub_f32_e32 v247, v212, v251
	v_exp_f32_e32 v250, v247
	v_add_f32_e32 v247, 0x41000000, v212
	v_cmp_gt_f32_e32 vcc, v246, v247
	s_cmp_eq_u64 vcc, 0
	v_mul_f32_e32 v246, v100, v250
	s_cselect_b64 s[0:1], -1, 0
	v_cndmask_b32_e64 v194, v246, v100, s[0:1]
	s_waitcnt lgkmcnt(4)
	v_mfma_f32_32x32x16_bf16 v[16:31], v[140:143], v[96:99], v[16:31]
	v_cndmask_b32_e64 v212, v251, v212, s[0:1]
	v_sub_f32_e32 v140, v92, v212
	v_sub_f32_e32 v141, v93, v212
	v_sub_f32_e32 v138, v90, v212
	v_sub_f32_e32 v139, v91, v212
	s_waitcnt lgkmcnt(3)
	v_mfma_f32_32x32x16_bf16 v[96:111], v[144:147], v[160:163], 0
	v_sub_f32_e32 v142, v94, v212
	v_sub_f32_e32 v143, v95, v212
	v_sub_f32_e32 v92, v80, v212
	v_sub_f32_e32 v93, v81, v212
	v_sub_f32_e32 v128, v82, v212
	v_sub_f32_e32 v129, v83, v212
	s_waitcnt lgkmcnt(2)
	v_mfma_f32_32x32x16_bf16 v[112:127], v[148:151], v[160:163], 0
	v_sub_f32_e32 v130, v68, v212
	v_sub_f32_e32 v131, v69, v212
	v_sub_f32_e32 v90, v64, v212
	v_sub_f32_e32 v91, v65, v212
	v_sub_f32_e32 v132, v84, v212
	v_sub_f32_e32 v133, v85, v212
	s_waitcnt lgkmcnt(1)
	v_mfma_f32_32x32x16_bf16 v[96:111], v[152:155], v[164:167], v[96:111]
	v_sub_f32_e32 v94, v66, v212
	v_sub_f32_e32 v95, v67, v212
	v_sub_f32_e32 v134, v86, v212
	v_sub_f32_e32 v135, v87, v212
	v_sub_f32_e32 v136, v88, v212
	v_sub_f32_e32 v137, v89, v212
	s_waitcnt lgkmcnt(0)
	v_mfma_f32_32x32x16_bf16 v[112:127], v[156:159], v[164:167], v[112:127]
	v_sub_f32_e32 v144, v70, v212
	v_sub_f32_e32 v145, v71, v212
	v_sub_f32_e32 v148, v74, v212
	v_sub_f32_e32 v149, v75, v212
	v_sub_f32_e32 v150, v76, v212
	v_sub_f32_e32 v151, v77, v212
	v_sub_f32_e32 v146, v72, v212
	v_sub_f32_e32 v147, v73, v212
	v_sub_f32_e32 v152, v78, v212
	v_sub_f32_e32 v153, v79, v212
	v_mov_b32_e32 v68, v250
	s_branch .Lattn_body_1

.LBB0_840:
	s_add_i32 s0, s78, 0xffff8000
	s_and_b32 s10, s0, 0x18000
	v_add_u32_e32 v76, s10, v237
	v_add_u32_e32 v76, v76, v228
	ds_read_b128 v[80:83], v76 offset:16384
	ds_read_b128 v[84:87], v76 offset:20480
	ds_read_b128 v[88:91], v76 offset:24576
	ds_read_b128 v[92:95], v76 offset:28672
	v_max3_f32 v68, v96, v97, v98
	v_max3_f32 v70, v104, v105, v106
	v_max3_f32 v71, v112, v113, v114
	v_max3_f32 v72, v120, v121, v122
	v_max3_f32 v68, v68, v99, v100
	v_max3_f32 v70, v70, v107, v108
	v_max3_f32 v71, v71, v115, v116
	v_max3_f32 v72, v72, v123, v124
	s_waitcnt lgkmcnt(3)
	v_mfma_f32_32x32x16_bf16 v[0:15], v[80:83], v[64:67], v[0:15]
	v_max3_f32 v68, v68, v101, v102
	v_max3_f32 v70, v70, v109, v110
	v_max3_f32 v71, v71, v117, v118
	v_max3_f32 v72, v72, v125, v126
	s_xor_b32 s33, s10, 0x10000
	v_max3_f32 v68, v68, v103, v70
	v_max3_f32 v70, v71, v119, v72
	s_waitcnt lgkmcnt(2)
	v_mfma_f32_32x32x16_bf16 v[48:63], v[84:87], v[64:67], v[48:63]
	v_max3_f32 v68, v68, v111, v127
	s_nop 0
	v_max3_f32 v68, v68, v70, v70
	s_nop 0
	v_mov_b32_e32 v70, v68
	s_nop 1
	v_permlane32_swap_b32_e32 v68, v70
	v_max3_f32 v68, v68, v70, v70
	s_nop 0
	v_max_f32_e32 v141, v212, v68
	s_waitcnt lgkmcnt(1)
	v_mfma_f32_32x32x16_bf16 v[32:47], v[88:91], v[64:67], v[32:47]
	v_sub_f32_e32 v70, v212, v141
	v_exp_f32_e32 v140, v70
	v_add_f32_e32 v70, 0x41000000, v212
	v_cmp_gt_f32_e32 vcc, v68, v70
	s_cmp_eq_u64 vcc, 0
	v_mul_f32_e32 v68, v69, v140
	s_cselect_b64 s[0:1], -1, 0
	v_cndmask_b32_e64 v194, v68, v69, s[0:1]
	s_waitcnt lgkmcnt(0)
	v_mfma_f32_32x32x16_bf16 v[16:31], v[92:95], v[64:67], v[16:31]
	v_add_u32_e32 v182, s10, v237
	v_add_u32_e32 v158, s33, v235
	v_add_u32_e32 v88, v158, v231
	v_add_u32_e32 v150, v182, v231
	v_add_u32_e32 v159, v158, v230
	v_cndmask_b32_e64 v212, v141, v212, s[0:1]
	v_add_u32_e32 v141, v182, v230
	v_sub_f32_e32 v180, v102, v212
	v_sub_f32_e32 v181, v103, v212
	v_sub_f32_e32 v116, v116, v212
	v_sub_f32_e32 v117, v117, v212
	v_sub_f32_e32 v108, v108, v212
	v_sub_f32_e32 v109, v109, v212
	v_sub_f32_e32 v124, v124, v212
	v_sub_f32_e32 v125, v125, v212
	v_exp_f32_e32 v116, v116
	v_exp_f32_e32 v117, v117
	v_exp_f32_e32 v108, v108
	v_exp_f32_e32 v124, v124
	v_exp_f32_e32 v109, v109
	v_add_u32_e32 v68, v158, v228
	v_add_u32_e32 v158, v158, v229
	v_exp_f32_e32 v125, v125
	v_sub_f32_e32 v114, v114, v212
	v_sub_f32_e32 v115, v115, v212
	v_sub_f32_e32 v118, v118, v212
	v_sub_f32_e32 v119, v119, v212
	v_sub_f32_e32 v122, v122, v212
	v_sub_f32_e32 v123, v123, v212
	v_sub_f32_e32 v110, v110, v212
	v_sub_f32_e32 v111, v111, v212
	ds_read_b128 v[64:67], v68
	ds_read_b128 v[80:83], v68 offset:4096
	ds_read_b128 v[84:87], v88
	ds_read_b128 v[142:145], v88 offset:4096
	v_sub_f32_e32 v126, v126, v212
	v_sub_f32_e32 v127, v127, v212
	v_sub_f32_e32 v106, v106, v212
	v_sub_f32_e32 v107, v107, v212
	v_exp_f32_e32 v114, v114
	v_exp_f32_e32 v115, v115
	v_exp_f32_e32 v118, v118
	s_waitcnt lgkmcnt(0)
	v_mfma_f32_32x32x16_bf16 v[64:79], v[64:67], v[160:163], 0
	v_exp_f32_e32 v119, v119
	v_exp_f32_e32 v122, v122
	v_exp_f32_e32 v123, v123
	v_exp_f32_e32 v110, v110
	v_exp_f32_e32 v126, v126
	v_exp_f32_e32 v111, v111
	v_exp_f32_e32 v127, v127
	v_mfma_f32_32x32x16_bf16 v[64:79], v[84:87], v[164:167], v[64:79]
	v_sub_f32_e32 v104, v104, v212
	v_sub_f32_e32 v105, v105, v212
	v_sub_f32_e32 v112, v112, v212
	v_sub_f32_e32 v113, v113, v212
	v_sub_f32_e32 v120, v120, v212
	v_sub_f32_e32 v121, v121, v212
	v_cvt_pk_bf16_f32 v183, v118, v119
	v_exp_f32_e32 v112, v112
	v_exp_f32_e32 v113, v113
	v_exp_f32_e32 v120, v120
	v_mfma_f32_32x32x16_bf16 v[80:95], v[80:83], v[160:163], 0
	v_exp_f32_e32 v121, v121
	v_cvt_pk_bf16_f32 v186, v108, v109
	v_cvt_pk_bf16_f32 v187, v110, v111
	v_mfma_f32_32x32x16_bf16 v[80:95], v[142:145], v[164:167], v[80:95]
	ds_read_b128 v[142:145], v150 offset:16384
	ds_read_b128 v[146:149], v150 offset:20480
	s_waitcnt lgkmcnt(0)
	v_mfma_f32_32x32x16_bf16 v[0:15], v[142:145], v[136:139], v[0:15]
	ds_read_b128 v[142:145], v150 offset:24576
	ds_read_b128 v[150:153], v150 offset:28672
	ds_read_b128 v[154:157], v159
	ds_read_b128 v[176:179], v159 offset:4096
	v_mfma_f32_32x32x16_bf16 v[48:63], v[146:149], v[136:139], v[48:63]
	ds_read_b128 v[146:149], v158
	ds_read_b128 v[238:241], v158 offset:4096
	v_sub_f32_e32 v158, v96, v212
	v_sub_f32_e32 v159, v97, v212
	s_waitcnt lgkmcnt(0)
	v_mfma_f32_32x32x16_bf16 v[32:47], v[142:145], v[136:139], v[32:47]
	v_sub_f32_e32 v142, v98, v212
	v_sub_f32_e32 v143, v99, v212
	v_sub_f32_e32 v144, v100, v212
	v_sub_f32_e32 v145, v101, v212
	ds_read_b128 v[96:99], v141 offset:16384
	ds_read_b128 v[100:103], v141 offset:20480
	s_waitcnt lgkmcnt(0)
	v_mfma_f32_32x32x16_bf16 v[0:15], v[96:99], v[132:135], v[0:15]
	ds_read_b128 v[96:99], v141 offset:24576
	v_mfma_f32_32x32x16_bf16 v[48:63], v[100:103], v[132:135], v[48:63]
	ds_read_b128 v[100:103], v141 offset:28672
	v_add_u32_e32 v141, v182, v229
	v_cvt_pk_bf16_f32 v182, v116, v117
	v_mfma_f32_32x32x16_bf16 v[16:31], v[150:153], v[136:139], v[16:31]
	v_exp_f32_e32 v138, v142
	v_exp_f32_e32 v139, v143
	v_exp_f32_e32 v142, v144
	v_exp_f32_e32 v143, v145
	v_exp_f32_e32 v144, v180
	v_exp_f32_e32 v145, v181
	v_exp_f32_e32 v136, v158
	s_waitcnt lgkmcnt(0)
	v_mfma_f32_32x32x16_bf16 v[32:47], v[96:99], v[132:135], v[32:47]
	ds_read_b128 v[96:99], v141 offset:16384
	v_exp_f32_e32 v137, v159
	v_cvt_pk_bf16_f32 v180, v112, v113
	v_cvt_pk_bf16_f32 v181, v114, v115
	v_add_f32_e32 v152, v136, v112
	v_add_f32_e32 v153, v137, v113
	v_mfma_f32_32x32x16_bf16 v[16:31], v[100:103], v[132:135], v[16:31]
	v_add_f32_e64 v100, v108, v124
	v_add_f32_e64 v101, v109, v125
	v_add_f32_e64 v102, v142, v116
	v_add_f32_e64 v103, v143, v117
	v_exp_f32_e32 v134, v106
	v_exp_f32_e32 v135, v107
	v_exp_f32_e32 v132, v104
	v_exp_f32_e32 v133, v105
	v_add_f32_e32 v106, v138, v114
	v_add_f32_e32 v107, v139, v115
	v_mfma_f32_32x32x16_bf16 v[64:79], v[154:157], v[168:171], v[64:79]
	v_add_f32_e64 v154, v102, v100
	v_add_f32_e64 v155, v103, v101
	ds_read_b128 v[100:103], v141 offset:20480
	v_add_f32_e64 v104, v134, v122
	v_add_f32_e64 v105, v135, v123
	v_add_f32_e32 v150, v132, v120
	v_add_f32_e32 v151, v133, v121
	v_add_f32_e32 v104, v106, v104
	v_add_f32_e32 v105, v107, v105
	v_cvt_pk_bf16_f32 v184, v132, v133
	v_cvt_pk_bf16_f32 v185, v134, v135
	v_mfma_f32_32x32x16_bf16 v[64:79], v[146:149], v[172:175], v[64:79]
	v_add_f32_e64 v146, v110, v126
	v_add_f32_e64 v147, v111, v127
	v_add_f32_e64 v148, v144, v118
	v_add_f32_e64 v149, v145, v119
	s_waitcnt lgkmcnt(0)
	v_mfma_f32_32x32x16_bf16 v[0:15], v[96:99], v[128:131], v[0:15]
	v_add_f32_e64 v98, v148, v146
	v_add_f32_e64 v99, v149, v147
	v_add_f32_e64 v96, v152, v150
	v_add_f32_e64 v97, v153, v151
	v_add_f32_e64 v98, v104, v98
	v_add_f32_e64 v99, v105, v99
	ds_read_b128 v[104:107], v141 offset:24576
	v_add_f32_e32 v96, v96, v154
	v_add_f32_e32 v97, v97, v155
	s_nop 0
	v_add_f32_e32 v96, v96, v97
	v_mfma_f32_32x32x16_bf16 v[48:63], v[100:103], v[128:131], v[48:63]
	ds_read_b128 v[100:103], v141 offset:28672
	v_add_f32_e32 v97, v98, v99
	v_add_f32_e32 v146, v96, v97
	v_cvt_pk_bf16_f32 v96, v136, v137
	v_cvt_pk_bf16_f32 v97, v138, v139
	v_cvt_pk_bf16_f32 v98, v142, v143
	v_cvt_pk_bf16_f32 v99, v144, v145
	v_mfma_f32_32x32x16_bf16 v[80:95], v[176:179], v[168:171], v[80:95]
	v_cvt_pk_bf16_f32 v176, v120, v121
	v_cvt_pk_bf16_f32 v177, v122, v123
	v_cvt_pk_bf16_f32 v178, v124, v125
	v_cvt_pk_bf16_f32 v179, v126, v127
	s_waitcnt lgkmcnt(0)
	v_mfma_f32_32x32x16_bf16 v[32:47], v[104:107], v[128:131], v[32:47]
	v_mfma_f32_32x32x16_bf16 v[16:31], v[100:103], v[128:131], v[16:31]
	v_add_f32_e32 v100, v194, v146
	v_mfma_f32_32x32x16_bf16 v[80:95], v[238:241], v[172:175], v[80:95]
	s_cbranch_vccz .LBB0_842
	v_pk_mul_f32 v[14:15], v[140:141], v[14:15] op_sel_hi:[0,1]
	v_pk_mul_f32 v[12:13], v[140:141], v[12:13] op_sel_hi:[0,1]
	v_pk_mul_f32 v[10:11], v[140:141], v[10:11] op_sel_hi:[0,1]
	v_pk_mul_f32 v[8:9], v[140:141], v[8:9] op_sel_hi:[0,1]
	v_pk_mul_f32 v[6:7], v[140:141], v[6:7] op_sel_hi:[0,1]
	v_pk_mul_f32 v[4:5], v[140:141], v[4:5] op_sel_hi:[0,1]
	v_pk_mul_f32 v[2:3], v[140:141], v[2:3] op_sel_hi:[0,1]
	v_pk_mul_f32 v[0:1], v[140:141], v[0:1] op_sel_hi:[0,1]
	v_pk_mul_f32 v[62:63], v[140:141], v[62:63] op_sel_hi:[0,1]
	v_pk_mul_f32 v[60:61], v[140:141], v[60:61] op_sel_hi:[0,1]
	v_pk_mul_f32 v[58:59], v[140:141], v[58:59] op_sel_hi:[0,1]
	v_pk_mul_f32 v[56:57], v[140:141], v[56:57] op_sel_hi:[0,1]
	v_pk_mul_f32 v[54:55], v[140:141], v[54:55] op_sel_hi:[0,1]
	v_pk_mul_f32 v[52:53], v[140:141], v[52:53] op_sel_hi:[0,1]
	v_pk_mul_f32 v[50:51], v[140:141], v[50:51] op_sel_hi:[0,1]
	v_pk_mul_f32 v[48:49], v[140:141], v[48:49] op_sel_hi:[0,1]
	v_pk_mul_f32 v[46:47], v[140:141], v[46:47] op_sel_hi:[0,1]
	v_pk_mul_f32 v[44:45], v[140:141], v[44:45] op_sel_hi:[0,1]
	v_pk_mul_f32 v[42:43], v[140:141], v[42:43] op_sel_hi:[0,1]
	v_pk_mul_f32 v[40:41], v[140:141], v[40:41] op_sel_hi:[0,1]
	v_pk_mul_f32 v[38:39], v[140:141], v[38:39] op_sel_hi:[0,1]
	v_pk_mul_f32 v[36:37], v[140:141], v[36:37] op_sel_hi:[0,1]
	v_pk_mul_f32 v[34:35], v[140:141], v[34:35] op_sel_hi:[0,1]
	v_pk_mul_f32 v[32:33], v[140:141], v[32:33] op_sel_hi:[0,1]
	v_pk_mul_f32 v[30:31], v[140:141], v[30:31] op_sel_hi:[0,1]
	v_pk_mul_f32 v[28:29], v[140:141], v[28:29] op_sel_hi:[0,1]
	v_pk_mul_f32 v[26:27], v[140:141], v[26:27] op_sel_hi:[0,1]
	v_pk_mul_f32 v[24:25], v[140:141], v[24:25] op_sel_hi:[0,1]
	v_pk_mul_f32 v[22:23], v[140:141], v[22:23] op_sel_hi:[0,1]
	v_pk_mul_f32 v[20:21], v[140:141], v[20:21] op_sel_hi:[0,1]
	v_pk_mul_f32 v[18:19], v[140:141], v[18:19] op_sel_hi:[0,1]
	v_pk_mul_f32 v[16:17], v[140:141], v[16:17] op_sel_hi:[0,1]

.Lattn2_nomask:
	s_add_i32 s9, s34, 0x10000
	s_and_b32 s33, s9, 0x18000
	s_and_b32 s10, s34, 0x18000
	v_add_u32_e32 v250, s33, v237
	v_add_u32_e32 v250, v250, v230
	ds_read_b128 v[128:131], v250 offset:16384
	ds_read_b128 v[132:135], v250 offset:20480
	ds_read_b128 v[136:139], v250 offset:24576
	ds_read_b128 v[140:143], v250 offset:28672
	v_add_u32_e32 v251, s10, v236
	v_add_u32_e32 v250, v251, v230
	ds_read_b128 v[144:147], v250
	ds_read_b128 v[148:151], v250 offset:4096
	v_add_u32_e32 v250, v251, v233
	ds_read_b128 v[152:155], v250
	ds_read_b128 v[156:159], v250 offset:4096
	s_add_i32 s0, s74, s64
	s_addk_i32 s0, 0xc0
	s_mul_i32 s0, s0, s14
	s_add_i32 s0, s0, s92
	s_addk_i32 s0, 0x1c00
	s_add_u32 s98, s82, s0
	s_addc_u32 s99, s83, 0
	s_lshl_b32 s1, s17, 13
	s_add_u32 s46, s76, s1
	s_addc_u32 s47, s77, 0
	s_add_i32 s0, s34, 0x8000
	s_and_b32 s0, s0, 0x18000
	s_add_i32 s0, s5, s0
	s_mov_b32 m0, s0
	s_nop 0
	global_load_lds_dwordx4 v244, s[98:99]
	s_add_i32 m0, s0, 0x2000
	s_add_u32 s98, s98, 0x80
	s_addc_u32 s99, s99, 0
	global_load_lds_dwordx4 v244, s[98:99]
	s_add_i32 m0, s0, 0x4000
	s_nop 0
	global_load_lds_dwordx4 v245, s[46:47]
	s_add_i32 m0, s0, 0x6000
	s_add_u32 s46, s46, 0x80000
	s_addc_u32 s47, s47, 0
	global_load_lds_dwordx4 v245, s[46:47]
	v_max3_f32 v246, v64, v65, v66
	v_max3_f32 v247, v72, v73, v74
	v_max3_f32 v248, v80, v81, v82
	v_max3_f32 v249, v88, v89, v90
	v_max3_f32 v246, v246, v67, v68
	v_max3_f32 v247, v247, v75, v76
	v_max3_f32 v248, v248, v83, v84
	v_max3_f32 v249, v249, v91, v92
	s_waitcnt lgkmcnt(7)
	v_mfma_f32_32x32x16_bf16 v[0:15], v[128:131], v[96:99], v[0:15]
	v_max3_f32 v246, v246, v69, v70
	v_max3_f32 v247, v247, v77, v78
	v_max3_f32 v248, v248, v85, v86
	v_max3_f32 v249, v249, v93, v94
	v_max3_f32 v246, v246, v71, v247
	v_max3_f32 v247, v248, v87, v249
	s_waitcnt lgkmcnt(6)
	v_mfma_f32_32x32x16_bf16 v[48:63], v[132:135], v[96:99], v[48:63]
	v_max3_f32 v246, v246, v79, v95
	s_nop 0
	v_max3_f32 v246, v246, v247, v247
	s_nop 0
	v_mov_b32_e32 v247, v246
	s_nop 1
	v_permlane32_swap_b32_e32 v246, v247
	v_max3_f32 v246, v246, v247, v247
	s_nop 0
	v_max_f32_e32 v251, v214, v246
	s_waitcnt lgkmcnt(5)
	v_mfma_f32_32x32x16_bf16 v[32:47], v[136:139], v[96:99], v[32:47]
	v_sub_f32_e32 v247, v214, v251
	v_exp_f32_e32 v250, v247
	v_add_f32_e32 v247, 0x41000000, v214
	v_cmp_gt_f32_e32 vcc, v246, v247
	s_cmp_eq_u64 vcc, 0
	v_mul_f32_e32 v246, v100, v250
	s_cselect_b64 s[0:1], -1, 0
	v_cndmask_b32_e64 v194, v246, v100, s[0:1]
	s_waitcnt lgkmcnt(4)
	v_mfma_f32_32x32x16_bf16 v[16:31], v[140:143], v[96:99], v[16:31]
	v_cndmask_b32_e64 v214, v251, v214, s[0:1]
	v_sub_f32_e32 v140, v92, v214
	v_sub_f32_e32 v141, v93, v214
	v_sub_f32_e32 v138, v90, v214
	v_sub_f32_e32 v139, v91, v214
	s_waitcnt lgkmcnt(3)
	v_mfma_f32_32x32x16_bf16 v[96:111], v[144:147], v[160:163], 0
	v_sub_f32_e32 v142, v94, v214
	v_sub_f32_e32 v143, v95, v214
	v_sub_f32_e32 v92, v80, v214
	v_sub_f32_e32 v93, v81, v214
	v_sub_f32_e32 v128, v82, v214
	v_sub_f32_e32 v129, v83, v214
	s_waitcnt lgkmcnt(2)
	v_mfma_f32_32x32x16_bf16 v[112:127], v[148:151], v[160:163], 0
	v_sub_f32_e32 v130, v68, v214
	v_sub_f32_e32 v131, v69, v214
	v_sub_f32_e32 v90, v64, v214
	v_sub_f32_e32 v91, v65, v214
	v_sub_f32_e32 v132, v84, v214
	v_sub_f32_e32 v133, v85, v214
	s_waitcnt lgkmcnt(1)
	v_mfma_f32_32x32x16_bf16 v[96:111], v[152:155], v[164:167], v[96:111]
	v_sub_f32_e32 v94, v66, v214
	v_sub_f32_e32 v95, v67, v214
	v_sub_f32_e32 v134, v86, v214
	v_sub_f32_e32 v135, v87, v214
	v_sub_f32_e32 v136, v88, v214
	v_sub_f32_e32 v137, v89, v214
	s_waitcnt lgkmcnt(0)
	v_mfma_f32_32x32x16_bf16 v[112:127], v[156:159], v[164:167], v[112:127]
	v_sub_f32_e32 v144, v70, v214
	v_sub_f32_e32 v145, v71, v214
	v_sub_f32_e32 v148, v74, v214
	v_sub_f32_e32 v149, v75, v214
	v_sub_f32_e32 v150, v76, v214
	v_sub_f32_e32 v151, v77, v214
	v_sub_f32_e32 v146, v72, v214
	v_sub_f32_e32 v147, v73, v214
	v_sub_f32_e32 v152, v78, v214
	v_sub_f32_e32 v153, v79, v214
	v_mov_b32_e32 v68, v250
	s_branch .Lattn_body_2

.LBB0_870:
	s_add_i32 s0, s34, 0xffff8000
	s_and_b32 s33, s0, 0x18000
	v_add_u32_e32 v76, s33, v237
	v_add_u32_e32 v76, v76, v230
	ds_read_b128 v[80:83], v76 offset:16384
	ds_read_b128 v[84:87], v76 offset:20480
	ds_read_b128 v[88:91], v76 offset:24576
	ds_read_b128 v[92:95], v76 offset:28672
	v_max3_f32 v68, v96, v97, v98
	v_max3_f32 v70, v104, v105, v106
	v_max3_f32 v71, v112, v113, v114
	v_max3_f32 v72, v120, v121, v122
	v_max3_f32 v68, v68, v99, v100
	v_max3_f32 v70, v70, v107, v108
	v_max3_f32 v71, v71, v115, v116
	v_max3_f32 v72, v72, v123, v124
	s_waitcnt lgkmcnt(3)
	v_mfma_f32_32x32x16_bf16 v[0:15], v[80:83], v[64:67], v[0:15]
	v_max3_f32 v68, v68, v101, v102
	v_max3_f32 v70, v70, v109, v110
	v_max3_f32 v71, v71, v117, v118
	v_max3_f32 v72, v72, v125, v126
	s_xor_b32 s34, s33, 0x10000
	v_max3_f32 v68, v68, v103, v70
	v_max3_f32 v70, v71, v119, v72
	s_waitcnt lgkmcnt(2)
	v_mfma_f32_32x32x16_bf16 v[48:63], v[84:87], v[64:67], v[48:63]
	v_max3_f32 v68, v68, v111, v127
	s_nop 0
	v_max3_f32 v68, v68, v70, v70
	s_nop 0
	v_mov_b32_e32 v70, v68
	s_nop 1
	v_permlane32_swap_b32_e32 v68, v70
	v_max3_f32 v68, v68, v70, v70
	s_nop 0
	v_max_f32_e32 v141, v214, v68
	s_waitcnt lgkmcnt(1)
	v_mfma_f32_32x32x16_bf16 v[32:47], v[88:91], v[64:67], v[32:47]
	v_sub_f32_e32 v70, v214, v141
	v_exp_f32_e32 v140, v70
	v_add_f32_e32 v70, 0x41000000, v214
	v_cmp_gt_f32_e32 vcc, v68, v70
	s_cmp_eq_u64 vcc, 0
	v_mul_f32_e32 v68, v69, v140
	s_cselect_b64 s[0:1], -1, 0
	v_cndmask_b32_e64 v194, v68, v69, s[0:1]
	s_waitcnt lgkmcnt(0)
	v_mfma_f32_32x32x16_bf16 v[16:31], v[92:95], v[64:67], v[16:31]
	v_add_u32_e32 v182, s33, v237
	v_add_u32_e32 v158, s34, v236
	v_add_u32_e32 v88, v158, v233
	v_add_u32_e32 v150, v182, v233
	v_add_u32_e32 v159, v158, v232
	v_cndmask_b32_e64 v214, v141, v214, s[0:1]
	v_add_u32_e32 v141, v182, v232
	v_sub_f32_e32 v180, v102, v214
	v_sub_f32_e32 v181, v103, v214
	v_sub_f32_e32 v116, v116, v214
	v_sub_f32_e32 v117, v117, v214
	v_sub_f32_e32 v108, v108, v214
	v_sub_f32_e32 v109, v109, v214
	v_sub_f32_e32 v124, v124, v214
	v_sub_f32_e32 v125, v125, v214
	v_exp_f32_e32 v116, v116
	v_exp_f32_e32 v117, v117
	v_exp_f32_e32 v108, v108
	v_exp_f32_e32 v124, v124
	v_exp_f32_e32 v109, v109
	v_add_u32_e32 v68, v158, v230
	v_add_u32_e32 v158, v158, v231
	v_exp_f32_e32 v125, v125
	v_sub_f32_e32 v114, v114, v214
	v_sub_f32_e32 v115, v115, v214
	v_sub_f32_e32 v118, v118, v214
	v_sub_f32_e32 v119, v119, v214
	v_sub_f32_e32 v122, v122, v214
	v_sub_f32_e32 v123, v123, v214
	v_sub_f32_e32 v110, v110, v214
	v_sub_f32_e32 v111, v111, v214
	ds_read_b128 v[64:67], v68
	ds_read_b128 v[80:83], v68 offset:4096
	ds_read_b128 v[84:87], v88
	ds_read_b128 v[142:145], v88 offset:4096
	v_sub_f32_e32 v126, v126, v214
	v_sub_f32_e32 v127, v127, v214
	v_sub_f32_e32 v106, v106, v214
	v_sub_f32_e32 v107, v107, v214
	v_exp_f32_e32 v114, v114
	v_exp_f32_e32 v115, v115
	v_exp_f32_e32 v118, v118
	s_waitcnt lgkmcnt(0)
	v_mfma_f32_32x32x16_bf16 v[64:79], v[64:67], v[160:163], 0
	v_exp_f32_e32 v119, v119
	v_exp_f32_e32 v122, v122
	v_exp_f32_e32 v123, v123
	v_exp_f32_e32 v110, v110
	v_exp_f32_e32 v126, v126
	v_exp_f32_e32 v111, v111
	v_exp_f32_e32 v127, v127
	v_mfma_f32_32x32x16_bf16 v[64:79], v[84:87], v[164:167], v[64:79]
	v_sub_f32_e32 v104, v104, v214
	v_sub_f32_e32 v105, v105, v214
	v_sub_f32_e32 v112, v112, v214
	v_sub_f32_e32 v113, v113, v214
	v_sub_f32_e32 v120, v120, v214
	v_sub_f32_e32 v121, v121, v214
	v_cvt_pk_bf16_f32 v183, v118, v119
	v_exp_f32_e32 v112, v112
	v_exp_f32_e32 v113, v113
	v_exp_f32_e32 v120, v120
	v_mfma_f32_32x32x16_bf16 v[80:95], v[80:83], v[160:163], 0
	v_exp_f32_e32 v121, v121
	v_cvt_pk_bf16_f32 v186, v108, v109
	v_cvt_pk_bf16_f32 v187, v110, v111
	v_mfma_f32_32x32x16_bf16 v[80:95], v[142:145], v[164:167], v[80:95]
	ds_read_b128 v[142:145], v150 offset:16384
	ds_read_b128 v[146:149], v150 offset:20480
	s_waitcnt lgkmcnt(0)
	v_mfma_f32_32x32x16_bf16 v[0:15], v[142:145], v[136:139], v[0:15]
	ds_read_b128 v[142:145], v150 offset:24576
	ds_read_b128 v[150:153], v150 offset:28672
	ds_read_b128 v[154:157], v159
	ds_read_b128 v[176:179], v159 offset:4096
	v_mfma_f32_32x32x16_bf16 v[48:63], v[146:149], v[136:139], v[48:63]
	ds_read_b128 v[146:149], v158
	ds_read_b128 v[238:241], v158 offset:4096
	v_sub_f32_e32 v158, v96, v214
	v_sub_f32_e32 v159, v97, v214
	s_waitcnt lgkmcnt(0)
	v_mfma_f32_32x32x16_bf16 v[32:47], v[142:145], v[136:139], v[32:47]
	v_sub_f32_e32 v142, v98, v214
	v_sub_f32_e32 v143, v99, v214
	v_sub_f32_e32 v144, v100, v214
	v_sub_f32_e32 v145, v101, v214
	ds_read_b128 v[96:99], v141 offset:16384
	ds_read_b128 v[100:103], v141 offset:20480
	s_waitcnt lgkmcnt(0)
	v_mfma_f32_32x32x16_bf16 v[0:15], v[96:99], v[132:135], v[0:15]
	ds_read_b128 v[96:99], v141 offset:24576
	v_mfma_f32_32x32x16_bf16 v[48:63], v[100:103], v[132:135], v[48:63]
	ds_read_b128 v[100:103], v141 offset:28672
	v_add_u32_e32 v141, v182, v231
	v_cvt_pk_bf16_f32 v182, v116, v117
	v_mfma_f32_32x32x16_bf16 v[16:31], v[150:153], v[136:139], v[16:31]
	v_exp_f32_e32 v138, v142
	v_exp_f32_e32 v139, v143
	v_exp_f32_e32 v142, v144
	v_exp_f32_e32 v143, v145
	v_exp_f32_e32 v144, v180
	v_exp_f32_e32 v145, v181
	v_exp_f32_e32 v136, v158
	s_waitcnt lgkmcnt(0)
	v_mfma_f32_32x32x16_bf16 v[32:47], v[96:99], v[132:135], v[32:47]
	ds_read_b128 v[96:99], v141 offset:16384
	v_exp_f32_e32 v137, v159
	v_cvt_pk_bf16_f32 v180, v112, v113
	v_cvt_pk_bf16_f32 v181, v114, v115
	v_add_f32_e32 v152, v136, v112
	v_add_f32_e32 v153, v137, v113
	v_mfma_f32_32x32x16_bf16 v[16:31], v[100:103], v[132:135], v[16:31]
	v_add_f32_e64 v100, v108, v124
	v_add_f32_e64 v101, v109, v125
	v_add_f32_e64 v102, v142, v116
	v_add_f32_e64 v103, v143, v117
	v_exp_f32_e32 v134, v106
	v_exp_f32_e32 v135, v107
	v_exp_f32_e32 v132, v104
	v_exp_f32_e32 v133, v105
	v_add_f32_e32 v106, v138, v114
	v_add_f32_e32 v107, v139, v115
	v_mfma_f32_32x32x16_bf16 v[64:79], v[154:157], v[168:171], v[64:79]
	v_add_f32_e64 v154, v102, v100
	v_add_f32_e64 v155, v103, v101
	ds_read_b128 v[100:103], v141 offset:20480
	v_add_f32_e64 v104, v134, v122
	v_add_f32_e64 v105, v135, v123
	v_add_f32_e32 v150, v132, v120
	v_add_f32_e32 v151, v133, v121
	v_add_f32_e32 v104, v106, v104
	v_add_f32_e32 v105, v107, v105
	v_cvt_pk_bf16_f32 v184, v132, v133
	v_cvt_pk_bf16_f32 v185, v134, v135
	v_mfma_f32_32x32x16_bf16 v[64:79], v[146:149], v[172:175], v[64:79]
	v_add_f32_e64 v146, v110, v126
	v_add_f32_e64 v147, v111, v127
	v_add_f32_e64 v148, v144, v118
	v_add_f32_e64 v149, v145, v119
	s_waitcnt lgkmcnt(0)
	v_mfma_f32_32x32x16_bf16 v[0:15], v[96:99], v[128:131], v[0:15]
	v_add_f32_e64 v98, v148, v146
	v_add_f32_e64 v99, v149, v147
	v_add_f32_e64 v96, v152, v150
	v_add_f32_e64 v97, v153, v151
	v_add_f32_e64 v98, v104, v98
	v_add_f32_e64 v99, v105, v99
	ds_read_b128 v[104:107], v141 offset:24576
	v_add_f32_e32 v96, v96, v154
	v_add_f32_e32 v97, v97, v155
	s_nop 0
	v_add_f32_e32 v96, v96, v97
	v_mfma_f32_32x32x16_bf16 v[48:63], v[100:103], v[128:131], v[48:63]
	ds_read_b128 v[100:103], v141 offset:28672
	v_add_f32_e32 v97, v98, v99
	v_add_f32_e32 v146, v96, v97
	v_cvt_pk_bf16_f32 v96, v136, v137
	v_cvt_pk_bf16_f32 v97, v138, v139
	v_cvt_pk_bf16_f32 v98, v142, v143
	v_cvt_pk_bf16_f32 v99, v144, v145
	v_mfma_f32_32x32x16_bf16 v[80:95], v[176:179], v[168:171], v[80:95]
	v_cvt_pk_bf16_f32 v176, v120, v121
	v_cvt_pk_bf16_f32 v177, v122, v123
	v_cvt_pk_bf16_f32 v178, v124, v125
	v_cvt_pk_bf16_f32 v179, v126, v127
	s_waitcnt lgkmcnt(0)
	v_mfma_f32_32x32x16_bf16 v[32:47], v[104:107], v[128:131], v[32:47]
	v_mfma_f32_32x32x16_bf16 v[16:31], v[100:103], v[128:131], v[16:31]
	v_add_f32_e32 v100, v194, v146
	v_mfma_f32_32x32x16_bf16 v[80:95], v[238:241], v[172:175], v[80:95]
	s_cbranch_vccz .LBB0_872
	v_pk_mul_f32 v[14:15], v[140:141], v[14:15] op_sel_hi:[0,1]
	v_pk_mul_f32 v[12:13], v[140:141], v[12:13] op_sel_hi:[0,1]
	v_pk_mul_f32 v[10:11], v[140:141], v[10:11] op_sel_hi:[0,1]
	v_pk_mul_f32 v[8:9], v[140:141], v[8:9] op_sel_hi:[0,1]
	v_pk_mul_f32 v[6:7], v[140:141], v[6:7] op_sel_hi:[0,1]
	v_pk_mul_f32 v[4:5], v[140:141], v[4:5] op_sel_hi:[0,1]
	v_pk_mul_f32 v[2:3], v[140:141], v[2:3] op_sel_hi:[0,1]
	v_pk_mul_f32 v[0:1], v[140:141], v[0:1] op_sel_hi:[0,1]
	v_pk_mul_f32 v[62:63], v[140:141], v[62:63] op_sel_hi:[0,1]
	v_pk_mul_f32 v[60:61], v[140:141], v[60:61] op_sel_hi:[0,1]
	v_pk_mul_f32 v[58:59], v[140:141], v[58:59] op_sel_hi:[0,1]
	v_pk_mul_f32 v[56:57], v[140:141], v[56:57] op_sel_hi:[0,1]
	v_pk_mul_f32 v[54:55], v[140:141], v[54:55] op_sel_hi:[0,1]
	v_pk_mul_f32 v[52:53], v[140:141], v[52:53] op_sel_hi:[0,1]
	v_pk_mul_f32 v[50:51], v[140:141], v[50:51] op_sel_hi:[0,1]
	v_pk_mul_f32 v[48:49], v[140:141], v[48:49] op_sel_hi:[0,1]
	v_pk_mul_f32 v[46:47], v[140:141], v[46:47] op_sel_hi:[0,1]
	v_pk_mul_f32 v[44:45], v[140:141], v[44:45] op_sel_hi:[0,1]
	v_pk_mul_f32 v[42:43], v[140:141], v[42:43] op_sel_hi:[0,1]
	v_pk_mul_f32 v[40:41], v[140:141], v[40:41] op_sel_hi:[0,1]
	v_pk_mul_f32 v[38:39], v[140:141], v[38:39] op_sel_hi:[0,1]
	v_pk_mul_f32 v[36:37], v[140:141], v[36:37] op_sel_hi:[0,1]
	v_pk_mul_f32 v[34:35], v[140:141], v[34:35] op_sel_hi:[0,1]
	v_pk_mul_f32 v[32:33], v[140:141], v[32:33] op_sel_hi:[0,1]
	v_pk_mul_f32 v[30:31], v[140:141], v[30:31] op_sel_hi:[0,1]
	v_pk_mul_f32 v[28:29], v[140:141], v[28:29] op_sel_hi:[0,1]
	v_pk_mul_f32 v[26:27], v[140:141], v[26:27] op_sel_hi:[0,1]
	v_pk_mul_f32 v[24:25], v[140:141], v[24:25] op_sel_hi:[0,1]
	v_pk_mul_f32 v[22:23], v[140:141], v[22:23] op_sel_hi:[0,1]
	v_pk_mul_f32 v[20:21], v[140:141], v[20:21] op_sel_hi:[0,1]
	v_pk_mul_f32 v[18:19], v[140:141], v[18:19] op_sel_hi:[0,1]
	v_pk_mul_f32 v[16:17], v[140:141], v[16:17] op_sel_hi:[0,1]
